# spatial gating: XOR-swizzled LDS image (conflict-free transposed writes), per-lane read addresses
# speedup vs baseline: 1.0140x; 1.0060x over previous
.LBB0_238:
	s_andn2_b64 vcc, exec, s[24:25]
	s_cbranch_vccnz .LBB0_245
	s_lshl_b32 s24, s12, 9
	s_ashr_i32 s25, s24, 31
	s_lshl_b64 s[24:25], s[24:25], 2
	v_lshlrev_b32_e32 v25, 3, v204
	s_add_u32 s20, s20, s24
	v_and_b32_e32 v26, 56, v25
	s_addc_u32 s21, s21, s25
	v_lshlrev_b32_e32 v28, 2, v26
	v_mov_b32_e32 v29, v81
	v_lshl_add_u64 v[38:39], s[20:21], 0, v[28:29]
	s_movk_i32 s10, 0x110
	v_ashrrev_i32_e32 v28, 2, v204
	v_ashrrev_i32_e32 v24, 2, v24
	v_mad_u32_u24 v25, v26, s10, 0
	v_add_u32_e32 v27, 0, v140
	v_and_b32_e32 v28, -2, v28
	v_and_b32_e32 v24, -2, v24
	v_mul_u32_u24_e32 v29, 0x110, v142
	s_add_i32 s10, s70, s66
	v_or_b32_e32 v32, v32, v142
	v_lshlrev_b32_e32 v36, 2, v141
	v_lshl_add_u64 v[40:41], s[36:37], 0, v[80:81]
	s_lshl_b32 s24, s66, 4
	s_lshl_b32 s25, s70, 4
	s_lshl_b32 s35, s10, 6
	s_lshl_b32 s36, s66, 6
	v_add_u32_e32 v55, v25, v28
	v_add_u32_e32 v56, v25, v24
	v_lshlrev_b32_e32 v42, 1, v26
	v_add_u32_e32 v57, v27, v29
	s_mov_b32 s37, s70
	s_and_b64 vcc, exec, s[8:9]
	s_cbranch_vccnz .LBB0_241
	s_load_dwordx2 s[88:89], s[0:1], 0xc0
	s_and_b32 s90, s37, 7
	s_lshl_b32 s90, s90, 8
	s_mov_b32 s91, 0
	v_lshl_add_u64 v[78:79], v[38:39], 0, s[90:91]
	global_load_dwordx4 v[70:73], v[78:79], off offset:16
	global_load_dwordx4 v[74:77], v[78:79], off
	s_waitcnt lgkmcnt(0)
	v_and_b32_e32 v188, 7, v204
	v_lshlrev_b32_e32 v188, 4, v188
	v_xor_b32_e32 v190, v55, v188
	v_xor_b32_e32 v191, v56, v188
	v_and_b32_e32 v186, 15, v229
	v_lshrrev_b32_e32 v187, 4, v229
	v_lshrrev_b32_e32 v188, 3, v186
	v_mul_u32_u24_e32 v189, 0x110, v186
	v_add_u32_e32 v208, 0, v187
	v_add_u32_e32 v184, 0, v188
	v_xor_b32_e32 v208, v208, v184
	v_lshl_add_u32 v208, v208, 4, v189
	v_add_u32_e32 v209, 4, v187
	v_add_u32_e32 v184, 0, v188
	v_xor_b32_e32 v209, v209, v184
	v_lshl_add_u32 v209, v209, 4, v189
	v_add_u32_e32 v210, 8, v187
	v_add_u32_e32 v184, 0, v188
	v_xor_b32_e32 v210, v210, v184
	v_lshl_add_u32 v210, v210, 4, v189
	v_add_u32_e32 v211, 12, v187
	v_add_u32_e32 v184, 0, v188
	v_xor_b32_e32 v211, v211, v184
	v_lshl_add_u32 v211, v211, 4, v189
	v_add_u32_e32 v212, 0, v187
	v_add_u32_e32 v184, 2, v188
	v_xor_b32_e32 v212, v212, v184
	v_lshl_add_u32 v212, v212, 4, v189
	v_add_u32_e32 v212, 4352, v212
	v_add_u32_e32 v213, 4, v187
	v_add_u32_e32 v184, 2, v188
	v_xor_b32_e32 v213, v213, v184
	v_lshl_add_u32 v213, v213, 4, v189
	v_add_u32_e32 v213, 4352, v213
	v_add_u32_e32 v214, 8, v187
	v_add_u32_e32 v184, 2, v188
	v_xor_b32_e32 v214, v214, v184
	v_lshl_add_u32 v214, v214, 4, v189
	v_add_u32_e32 v214, 4352, v214
	v_add_u32_e32 v215, 12, v187
	v_add_u32_e32 v184, 2, v188
	v_xor_b32_e32 v215, v215, v184
	v_lshl_add_u32 v215, v215, 4, v189
	v_add_u32_e32 v215, 4352, v215
	v_add_u32_e32 v216, 0, v187
	v_add_u32_e32 v184, 4, v188
	v_xor_b32_e32 v216, v216, v184
	v_lshl_add_u32 v216, v216, 4, v189
	v_add_u32_e32 v216, 8704, v216
	v_add_u32_e32 v217, 4, v187
	v_add_u32_e32 v184, 4, v188
	v_xor_b32_e32 v217, v217, v184
	v_lshl_add_u32 v217, v217, 4, v189
	v_add_u32_e32 v217, 8704, v217
	v_add_u32_e32 v218, 8, v187
	v_add_u32_e32 v184, 4, v188
	v_xor_b32_e32 v218, v218, v184
	v_lshl_add_u32 v218, v218, 4, v189
	v_add_u32_e32 v218, 8704, v218
	v_add_u32_e32 v219, 12, v187
	v_add_u32_e32 v184, 4, v188
	v_xor_b32_e32 v219, v219, v184
	v_lshl_add_u32 v219, v219, 4, v189
	v_add_u32_e32 v219, 8704, v219
	v_add_u32_e32 v220, 0, v187
	v_add_u32_e32 v184, 6, v188
	v_xor_b32_e32 v220, v220, v184
	v_lshl_add_u32 v220, v220, 4, v189
	v_add_u32_e32 v220, 13056, v220
	v_add_u32_e32 v221, 4, v187
	v_add_u32_e32 v184, 6, v188
	v_xor_b32_e32 v221, v221, v184
	v_lshl_add_u32 v221, v221, 4, v189
	v_add_u32_e32 v221, 13056, v221
	v_add_u32_e32 v222, 8, v187
	v_add_u32_e32 v184, 6, v188
	v_xor_b32_e32 v222, v222, v184
	v_lshl_add_u32 v222, v222, 4, v189
	v_add_u32_e32 v222, 13056, v222
	v_add_u32_e32 v223, 12, v187
	v_add_u32_e32 v184, 6, v188
	v_xor_b32_e32 v223, v223, v184
	v_lshl_add_u32 v223, v223, 4, v189
	v_add_u32_e32 v223, 13056, v223
	s_branch .Lsp_241

.Lsp_241:
	s_and_b32 s10, s25, 0xffffff80
	s_and_b32 s38, s37, 7
	v_add_u32_e32 v52, s10, v32
	v_mov_b64_e32 v[24:25], s[4:5]
	s_movk_i32 s10, 0xe00
	v_mad_i64_i32 v[24:25], s[20:21], v52, s10, v[24:25]
	s_lshl_b32 s10, s38, 7
	v_lshl_add_u64 v[24:25], v[24:25], 0, s[10:11]
	v_lshlrev_b32_e32 v80, 1, v36
	v_lshl_add_u64 v[24:25], v[24:25], 0, v[80:81]
	global_load_dwordx2 v[50:51], v[24:25], off offset:1536
	global_load_dwordx2 v[48:49], v[24:25], off offset:1568
	global_load_dwordx2 v[46:47], v[24:25], off offset:1600
	global_load_dwordx2 v[44:45], v[24:25], off offset:1632
	s_nop 0
	s_nop 0
	s_waitcnt vmcnt(4)
	v_lshlrev_b32_e32 v53, 16, v0
	v_mul_f32_e32 v53, v54, v53
	s_add_i32 s37, s37, s66
	s_cmpk_gt_i32 s37, 0x5ff
	s_cselect_b64 s[20:21], -1, 0
	s_and_b64 vcc, exec, s[20:21]
	v_mul_f32_e32 v53, v53, v74
	v_cvt_pk_bf16_f32 v53, v53, s0
	ds_write_b16 v190, v53
	v_and_b32_e32 v53, 0xffff0000, v0
	v_mul_f32_e32 v53, v54, v53
	v_mul_f32_e32 v53, v53, v75
	v_cvt_pk_bf16_f32 v53, v53, s0
	ds_write_b16 v190, v53 offset:272
	v_lshlrev_b32_e32 v53, 16, v1
	v_mul_f32_e32 v53, v54, v53
	v_mul_f32_e32 v53, v53, v76
	v_cvt_pk_bf16_f32 v53, v53, s0
	ds_write_b16 v190, v53 offset:544
	v_and_b32_e32 v53, 0xffff0000, v1
	v_mul_f32_e32 v53, v54, v53
	v_mul_f32_e32 v53, v53, v77
	v_cvt_pk_bf16_f32 v53, v53, s0
	ds_write_b16 v190, v53 offset:816
	v_lshlrev_b32_e32 v53, 16, v2
	v_mul_f32_e32 v53, v54, v53
	v_mul_f32_e32 v53, v53, v70
	v_cvt_pk_bf16_f32 v53, v53, s0
	ds_write_b16 v190, v53 offset:1088
	v_and_b32_e32 v53, 0xffff0000, v2
	v_mul_f32_e32 v53, v54, v53
	v_mul_f32_e32 v53, v53, v71
	v_cvt_pk_bf16_f32 v53, v53, s0
	ds_write_b16 v190, v53 offset:1360
	v_lshlrev_b32_e32 v53, 16, v3
	v_mul_f32_e32 v53, v54, v53
	v_mul_f32_e32 v53, v53, v72
	v_cvt_pk_bf16_f32 v53, v53, s0
	ds_write_b16 v190, v53 offset:1632
	v_and_b32_e32 v53, 0xffff0000, v3
	v_mul_f32_e32 v53, v54, v53
	v_mul_f32_e32 v53, v53, v73
	v_cvt_pk_bf16_f32 v53, v53, s0
	ds_write_b16 v190, v53 offset:1904
	v_lshlrev_b32_e32 v53, 16, v4
	v_mul_f32_e32 v53, v43, v53
	v_mul_f32_e32 v28, v53, v74
	v_cvt_pk_bf16_f32 v28, v28, s0
	ds_write_b16 v191, v28
	v_and_b32_e32 v28, 0xffff0000, v4
	v_mul_f32_e32 v28, v43, v28
	v_mul_f32_e32 v28, v28, v75
	v_cvt_pk_bf16_f32 v28, v28, s0
	ds_write_b16 v191, v28 offset:272
	v_lshlrev_b32_e32 v28, 16, v5
	v_mul_f32_e32 v28, v43, v28
	v_mul_f32_e32 v28, v28, v76
	v_cvt_pk_bf16_f32 v28, v28, s0
	ds_write_b16 v191, v28 offset:544
	v_and_b32_e32 v28, 0xffff0000, v5
	v_mul_f32_e32 v28, v43, v28
	v_mul_f32_e32 v28, v28, v77
	v_cvt_pk_bf16_f32 v28, v28, s0
	ds_write_b16 v191, v28 offset:816
	v_lshlrev_b32_e32 v28, 16, v6
	v_mul_f32_e32 v28, v43, v28
	v_mul_f32_e32 v24, v28, v70
	v_cvt_pk_bf16_f32 v24, v24, s0
	ds_write_b16 v191, v24 offset:1088
	v_and_b32_e32 v24, 0xffff0000, v6
	v_mul_f32_e32 v24, v43, v24
	v_mul_f32_e32 v24, v24, v71
	v_cvt_pk_bf16_f32 v24, v24, s0
	ds_write_b16 v191, v24 offset:1360
	v_lshlrev_b32_e32 v24, 16, v7
	v_mul_f32_e32 v24, v43, v24
	v_mul_f32_e32 v24, v24, v72
	v_cvt_pk_bf16_f32 v24, v24, s0
	ds_write_b16 v191, v24 offset:1632
	v_and_b32_e32 v24, 0xffff0000, v7
	v_mul_f32_e32 v24, v43, v24
	v_mul_f32_e32 v24, v24, v73
	v_cvt_pk_bf16_f32 v24, v24, s0
	ds_write_b16 v191, v24 offset:1904
	s_waitcnt lgkmcnt(0)
	s_barrier
	s_cbranch_vccnz .Lsp_243
	s_add_i32 s39, s24, s25
	s_and_b32 s39, s39, 0xffffff80
	v_add_u32_e32 v0, s39, v35
	v_mov_b64_e32 v[4:5], s[4:5]
	s_movk_i32 s43, 0xe00
	s_and_b32 s42, s35, 0x1c0
	v_mad_i64_i32 v[2:3], s[40:41], v0, s43, v[4:5]
	s_lshl_b32 s40, s42, 1
	s_mov_b32 s41, s11
	v_ashrrev_i32_e32 v1, 31, v0
	v_lshl_add_u64 v[2:3], v[2:3], 0, s[40:41]
	v_mov_b32_e32 v43, v81
	v_lshl_add_u64 v[2:3], v[2:3], 0, v[42:43]
	v_lshl_add_u64 v[6:7], v[0:1], 2, s[2:3]
	global_load_dwordx4 v[0:3], v[2:3], off offset:2560
	s_nop 0
	global_load_dword v54, v[6:7], off
	v_add_u32_e32 v6, s39, v37
	v_mad_i64_i32 v[4:5], s[42:43], v6, s43, v[4:5]
	v_lshl_add_u64 v[4:5], v[4:5], 0, s[40:41]
	v_ashrrev_i32_e32 v7, 31, v6
	v_lshl_add_u64 v[4:5], v[4:5], 0, v[42:43]
	v_lshl_add_u64 v[24:25], v[6:7], 2, s[2:3]
	global_load_dwordx4 v[4:7], v[4:5], off offset:2560
	s_nop 0
	global_load_dword v43, v[24:25], off
.Lsp_243:
	s_lshl_b32 s86, s38, 6
	ds_read_b128 v[82:85], v208
	ds_read_b128 v[86:89], v209
	ds_read_b128 v[90:93], v212
	ds_read_b128 v[94:97], v213
	ds_read_b128 v[98:101], v216
	ds_read_b128 v[102:105], v217
	ds_read_b128 v[106:109], v220
	ds_read_b128 v[110:113], v221
	v_ashrrev_i32_e32 v53, 31, v52
	v_lshlrev_b64 v[52:53], 11, v[52:53]
	s_add_i32 s25, s25, s24
	v_lshl_add_u64 v[52:53], s[88:89], 0, v[52:53]
	s_add_i32 s35, s35, s36
	s_waitcnt lgkmcnt(7)
	v_mfma_f32_16x16x32_bf16 v[24:27], v[82:85], v[8:11], 0
	ds_read_b128 v[114:117], v210
	s_waitcnt lgkmcnt(7)
	v_mfma_f32_16x16x32_bf16 v[24:27], v[86:89], v[12:15], v[24:27]
	ds_read_b128 v[118:121], v214
	s_waitcnt lgkmcnt(7)
	v_mfma_f32_16x16x32_bf16 v[28:31], v[90:93], v[8:11], 0
	ds_read_b128 v[122:125], v218
	s_waitcnt lgkmcnt(7)
	v_mfma_f32_16x16x32_bf16 v[28:31], v[94:97], v[12:15], v[28:31]
	ds_read_b128 v[126:129], v222
	s_waitcnt lgkmcnt(7)
	v_mfma_f32_16x16x32_bf16 v[58:61], v[98:101], v[8:11], 0
	ds_read_b128 v[130:133], v211
	s_waitcnt lgkmcnt(7)
	v_mfma_f32_16x16x32_bf16 v[58:61], v[102:105], v[12:15], v[58:61]
	ds_read_b128 v[134:137], v215
	s_waitcnt lgkmcnt(7)
	v_mfma_f32_16x16x32_bf16 v[62:65], v[106:109], v[8:11], 0
	ds_read_b128 v[150:153], v219
	s_waitcnt lgkmcnt(7)
	v_mfma_f32_16x16x32_bf16 v[62:65], v[110:113], v[12:15], v[62:65]
	ds_read_b128 v[154:157], v223
	s_waitcnt lgkmcnt(7)
	v_mfma_f32_16x16x32_bf16 v[24:27], v[114:117], v[16:19], v[24:27]
	s_waitcnt lgkmcnt(6)
	v_mfma_f32_16x16x32_bf16 v[28:31], v[118:121], v[16:19], v[28:31]
	s_waitcnt lgkmcnt(5)
	v_mfma_f32_16x16x32_bf16 v[58:61], v[122:125], v[16:19], v[58:61]
	s_waitcnt lgkmcnt(4)
	v_mfma_f32_16x16x32_bf16 v[62:65], v[126:129], v[16:19], v[62:65]
	s_waitcnt lgkmcnt(3)
	v_mfma_f32_16x16x32_bf16 v[24:27], v[130:133], v[20:23], v[24:27]
	s_waitcnt lgkmcnt(2)
	v_mfma_f32_16x16x32_bf16 v[28:31], v[134:137], v[20:23], v[28:31]
	s_waitcnt lgkmcnt(1)
	v_mfma_f32_16x16x32_bf16 v[58:61], v[150:153], v[20:23], v[58:61]
	s_waitcnt lgkmcnt(0)
	v_mfma_f32_16x16x32_bf16 v[62:65], v[154:157], v[20:23], v[62:65]
	s_and_b64 vcc, exec, s[20:21]
	s_cbranch_vccnz .Lsp_last
	s_waitcnt vmcnt(4)
	s_branch .Lsp_epi
